# gswap:9 on the la_lb2 stack: NSA head group flips every 2 units
# speedup vs baseline: 1.0102x; 1.0047x over previous
.LBB0_1007:
	s_mov_b32 s90, s20
	s_lshl_b32 s0, s23, 13
	s_lshl_b32 s1, s20, 4
	s_and_b32 s40, s22, 3
	s_bfe_u32 s29, s22, 0x10002
	s_bfe_u32 s98, s22, 0x10009
	s_xor_b32 s29, s29, s98
	s_lshl_b32 s74, s75, 4
	s_and_b32 s0, s0, 0x6000
	s_ashr_i32 s20, s1, 31
	s_add_u32 s0, s1, s0
	s_addc_u32 s1, s20, 0
	v_or_b32_e32 v0, s0, v130
	s_lshl_b32 s0, s23, 1
	v_mov_b32_e32 v1, s1
	s_and_b32 s0, s0, 8
	s_lshr_b32 s98, s23, 6
	s_and_b32 s98, s98, 8
	s_xor_b32 s0, s0, s98
	v_add_u32_e32 v4, s0, v131
	v_lshlrev_b64 v[0:1], 12, v[0:1]
	v_lshl_add_u64 v[0:1], s[36:37], 0, v[0:1]
	v_lshlrev_b32_e32 v2, 7, v4
	v_mov_b32_e32 v3, v123
	v_lshl_add_u64 v[2:3], v[0:1], 0, v[2:3]
	v_mov_b32_e32 v133, v123
	v_lshl_add_u64 v[2:3], v[2:3], 0, v[132:133]
	global_load_dwordx4 v[48:51], v[2:3], off
	global_load_dwordx4 v[52:55], v[2:3], off offset:64
	v_mul_u32_u24_e32 v2, 3, v4
	v_lshlrev_b32_e32 v2, 1, v2
	v_mov_b32_e32 v3, v123
	v_lshl_add_u64 v[0:1], v[0:1], 0, v[2:3]
	global_load_dword v133, v[0:1], off offset:3584
	global_load_ushort v185, v[0:1], off offset:3588
	v_lshl_add_u32 v184, s29, 3, v131
	v_add_u32_e32 v0, 1, v184
	v_cvt_f32_ubyte0_e32 v0, v0
	v_mul_f32_e32 v1, -0.5, v0
	v_cmp_gt_f32_e32 vcc, s64, v1
	s_lshl_b32 s0, s40, 1
	s_or_b32 s47, s0, s29
	v_cndmask_b32_e32 v1, 0, v177, vcc
	v_fmac_f32_e32 v1, -0.5, v0
	v_exp_f32_e32 v0, v1
	s_add_i32 s0, s75, -1
	s_ashr_i32 s0, s0, 6
	s_add_i32 s0, s0, 1
	v_cndmask_b32_e32 v1, 0, v178, vcc
	s_cmp_gt_i32 s75, 0
	v_ldexp_f32 v0, v0, v1
	s_cselect_b32 s20, s0, 0
	v_mov_b32_e32 v75, 0
	v_mul_f32_e32 v146, 0x3fb8aa3b, v0
	v_or_b32_e32 v144, s74, v130
	s_cmp_lt_i32 s20, 1
	v_add_u32_e32 v187, 0xa000, v152
	v_add_u32_e32 v186, 0xc800, v152
	v_mov_b32_e32 v74, 0
	v_mov_b32_e32 v73, 0
	v_mov_b32_e32 v72, 0
	v_mov_b32_e32 v79, 0
	v_mov_b32_e32 v78, 0
	v_mov_b32_e32 v77, 0
	v_mov_b32_e32 v76, 0
	v_mov_b32_e32 v71, 0
	v_mov_b32_e32 v70, 0
	v_mov_b32_e32 v69, 0
	v_mov_b32_e32 v68, 0
	v_mov_b32_e32 v67, 0
	v_mov_b32_e32 v66, 0
	v_mov_b32_e32 v65, 0
	v_mov_b32_e32 v64, 0
	v_mov_b32_e32 v80, 0
	v_mov_b32_e32 v81, 0
	s_cbranch_scc1 .LBB0_1027
	s_lshl_b32 s21, s47, 16
	s_add_u32 s0, s3, s21
	s_addc_u32 s1, s52, 0
	s_add_u32 s22, s53, s21
	s_addc_u32 s23, s54, 0
	s_add_i32 s21, s20, -1
	s_cmp_eq_u32 s20, 1
	s_cselect_b64 s[24:25], -1, 0
	s_and_b64 vcc, s[24:25], exec
	s_cselect_b32 s26, 0, 64
	s_lshl_b32 s24, s26, 7
	v_mov_b32_e32 v135, v123
	s_add_u32 s24, s0, s24
	v_lshl_add_u64 v[0:1], s[0:1], 0, v[134:135]
	v_mov_b32_e32 v137, v123
	s_addc_u32 s25, s1, 0
	s_lshl_b32 s26, s26, 1
	v_lshl_add_u64 v[44:45], v[0:1], 0, v[122:123]
	v_lshl_add_u64 v[0:1], s[22:23], 0, v[136:137]
	s_add_u32 s26, s22, s26
	v_lshl_add_u64 v[46:47], v[0:1], 0, v[122:123]
	s_addc_u32 s27, s23, 0
	v_lshl_add_u64 v[0:1], s[24:25], 0, v[134:135]
	v_mov_b32_e32 v8, v240
	v_mov_b32_e32 v9, v241
	v_mov_b32_e32 v10, v242
	v_mov_b32_e32 v11, v243
	v_mov_b32_e32 v12, v244
	v_mov_b32_e32 v13, v245
	v_mov_b32_e32 v14, v246
	v_mov_b32_e32 v15, v247
	v_lshl_add_u64 v[0:1], v[0:1], 0, v[122:123]
	v_lshl_add_u64 v[2:3], s[26:27], 0, v[136:137]
	v_lshl_add_u64 v[2:3], v[2:3], 0, v[122:123]
	v_mov_b32_e32 v16, v248
	v_mov_b32_e32 v17, v249
	v_mov_b32_e32 v18, v250
	v_mov_b32_e32 v19, v251
	v_mov_b32_e32 v20, v252
	v_mov_b32_e32 v21, v253
	v_mov_b32_e32 v22, v254
	v_mov_b32_e32 v23, v255
	s_min_u32 s26, s21, 2
	s_lshl_b32 s24, s26, 13
	s_add_u32 s24, s0, s24
	s_addc_u32 s25, s1, 0
	s_lshl_b32 s26, s26, 7
	s_add_u32 s26, s22, s26
	v_lshl_add_u64 v[0:1], s[24:25], 0, v[134:135]
	s_addc_u32 s27, s23, 0
	s_min_u32 s24, s21, 3
	s_lshl_b32 s25, s24, 13
	s_add_u32 s0, s0, s25
	v_lshl_add_u64 v[2:3], s[26:27], 0, v[136:137]
	s_addc_u32 s1, s1, 0
	s_lshl_b32 s24, s24, 7
	v_lshl_add_u64 v[0:1], v[0:1], 0, v[122:123]
	v_lshl_add_u64 v[2:3], v[2:3], 0, v[122:123]
	s_add_u32 s22, s22, s24
	global_load_dwordx4 v[4:7], v[0:1], off
	s_nop 0
	global_load_dwordx4 v[0:3], v[2:3], off
	v_lshl_add_u64 v[24:25], s[0:1], 0, v[134:135]
	s_addc_u32 s23, s23, 0
	v_lshl_add_u64 v[24:25], v[24:25], 0, v[122:123]
	v_lshl_add_u64 v[26:27], s[22:23], 0, v[136:137]
	v_lshl_add_u64 v[26:27], v[26:27], 0, v[122:123]
	v_mov_b32_e32 v75, 0
	s_mov_b32 s0, 0
	v_mov_b32_e32 v74, v75
	v_mov_b32_e32 v73, v75
	v_mov_b32_e32 v72, v75
	v_mov_b32_e32 v79, v75
	v_mov_b32_e32 v78, v75
	v_mov_b32_e32 v77, v75
	v_mov_b32_e32 v76, v75
	v_mov_b32_e32 v71, v75
	v_mov_b32_e32 v70, v75
	v_mov_b32_e32 v69, v75
	v_mov_b32_e32 v68, v75
	v_mov_b32_e32 v67, v75
	v_mov_b32_e32 v66, v75
	v_mov_b32_e32 v65, v75
	v_mov_b32_e32 v64, v75
	v_mov_b32_e32 v80, v75
	v_mov_b32_e32 v81, v75
	ds_write_b128 v151, v[8:11]
	ds_write2_b64 v187, v[12:13], v[14:15] offset1:2
	ds_write_b128 v151, v[16:19] offset:10240
	ds_write2_b64 v186, v[20:21], v[22:23] offset1:2
	global_load_dwordx4 v[12:15], v[24:25], off
	global_load_dwordx4 v[8:11], v[26:27], off
	s_waitcnt lgkmcnt(0)
	s_barrier
	s_cbranch_vccnz .LBB0_1021
	v_mov_b32_e32 v80, 0
	s_add_i32 s22, s75, -2
	v_mul_f32_e32 v82, 0x41800000, v146
	v_mul_f32_e32 v83, 0x42000000, v146
	v_mul_f32_e32 v84, 0x42400000, v146
	v_mul_f32_e32 v85, 0, v146
	s_waitcnt lgkmcnt(7)
	v_mul_f32_e32 v86, 0x43800000, v146
	v_mul_f32_e32 v87, 0x44000000, v146
	v_mul_f32_e32 v88, 0x44400000, v146
	v_add_u32_e32 v89, s74, v169
	s_mov_b32 s24, 5
	s_movk_i32 s23, 0xc0
	v_mov_b32_e32 v81, 0
	v_mov_b32_e32 v64, 0
	v_mov_b32_e32 v65, v80
	v_mov_b32_e32 v66, v80
	v_mov_b32_e32 v67, v80
	v_mov_b32_e32 v68, 0
	v_mov_b32_e32 v69, v80
	v_mov_b32_e32 v70, v80
	v_mov_b32_e32 v71, v80
	v_mov_b32_e32 v76, 0
	v_mov_b32_e32 v77, v80
	v_mov_b32_e32 v78, v80
	v_mov_b32_e32 v79, v80
	v_mov_b32_e32 v72, 0
	v_mov_b32_e32 v73, v80
	v_mov_b32_e32 v74, v80
	v_mov_b32_e32 v75, v80

.LBB0_1059:
	s_lshl_b32 s0, s80, 1
	s_add_u32 s0, s57, s0
	s_addc_u32 s1, s60, 0
	s_add_i32 s20, s74, 0xfffffe01
	s_andn2_b32 s20, s20, 63
	s_cmp_gt_i32 s75, 31
	s_cselect_b32 s20, s20, 0
	s_sub_i32 s21, s74, s20
	s_ashr_i32 s21, s21, 6
	s_min_i32 s22, s21, 0
	s_lshl_b32 s22, s22, 6
	s_add_i32 s22, s22, s20
	s_ashr_i32 s23, s22, 31
	s_lshl_b64 s[26:27], s[22:23], 12
	s_add_u32 s26, s24, s26
	s_addc_u32 s27, s25, s27
	s_lshl_b64 s[22:23], s[22:23], 1
	s_add_u32 s22, s0, s22
	s_addc_u32 s23, s1, s23
	v_mov_b32_e32 v141, v123
	s_waitcnt vmcnt(2)
	v_lshl_add_u64 v[18:19], s[22:23], 0, v[140:141]
	s_min_i32 s22, s21, 1
	s_lshl_b32 s22, s22, 6
	s_add_i32 s22, s22, s20
	v_mov_b32_e32 v139, v123
	s_ashr_i32 s23, s22, 31
	v_lshl_add_u64 v[16:17], s[26:27], 0, v[138:139]
	s_lshl_b64 s[26:27], s[22:23], 12
	s_add_u32 s26, s24, s26
	s_addc_u32 s27, s25, s27
	s_lshl_b64 s[22:23], s[22:23], 1
	s_add_u32 s22, s0, s22
	s_addc_u32 s23, s1, s23
	v_lshl_add_u64 v[16:17], v[16:17], 0, v[122:123]
	v_lshl_add_u64 v[20:21], v[18:19], 0, v[122:123]
	s_waitcnt vmcnt(0)
	v_lshl_add_u64 v[24:25], s[26:27], 0, v[138:139]
	v_lshl_add_u64 v[26:27], s[22:23], 0, v[140:141]
	v_mov_b32_e32 v16, v240
	v_mov_b32_e32 v17, v241
	v_mov_b32_e32 v18, v242
	v_mov_b32_e32 v19, v243
	s_nop 0
	v_mov_b32_e32 v20, v244
	v_mov_b32_e32 v21, v245
	v_mov_b32_e32 v22, v246
	v_mov_b32_e32 v23, v247
	v_lshl_add_u64 v[24:25], v[24:25], 0, v[122:123]
	v_lshl_add_u64 v[28:29], v[26:27], 0, v[122:123]
	v_mov_b32_e32 v24, v248
	v_mov_b32_e32 v25, v249
	v_mov_b32_e32 v26, v250
	v_mov_b32_e32 v27, v251
	s_nop 0
	v_mov_b32_e32 v28, v252
	v_mov_b32_e32 v29, v253
	v_mov_b32_e32 v30, v254
	v_mov_b32_e32 v31, v255
	s_min_i32 s22, s21, 2
	s_lshl_b32 s22, s22, 6
	s_add_i32 s22, s22, s20
	s_ashr_i32 s23, s22, 31
	s_lshl_b64 s[26:27], s[22:23], 12
	s_add_u32 s26, s24, s26
	s_addc_u32 s27, s25, s27
	s_lshl_b64 s[22:23], s[22:23], 1
	s_add_u32 s22, s0, s22
	s_waitcnt lgkmcnt(3)
	v_lshl_add_u64 v[32:33], s[26:27], 0, v[138:139]
	s_addc_u32 s23, s1, s23
	s_min_i32 s26, s21, 3
	v_lshl_add_u64 v[34:35], s[22:23], 0, v[140:141]
	s_lshl_b32 s22, s26, 6
	s_add_i32 s22, s22, s20
	s_ashr_i32 s23, s22, 31
	s_lshl_b64 s[26:27], s[22:23], 12
	s_add_u32 s24, s24, s26
	s_addc_u32 s25, s25, s27
	s_lshl_b64 s[22:23], s[22:23], 1
	s_add_u32 s22, s0, s22
	v_lshl_add_u64 v[32:33], v[32:33], 0, v[122:123]
	v_lshl_add_u64 v[34:35], v[34:35], 0, v[122:123]
	s_addc_u32 s23, s1, s23
	s_waitcnt lgkmcnt(2)
	global_load_dwordx4 v[36:39], v[32:33], off offset:3072
	s_nop 0
	global_load_dwordx4 v[32:35], v[34:35], off
	s_waitcnt lgkmcnt(1)
	v_lshl_add_u64 v[40:41], s[24:25], 0, v[138:139]
	v_lshl_add_u64 v[42:43], s[22:23], 0, v[140:141]
	v_lshl_add_u64 v[40:41], v[40:41], 0, v[122:123]
	v_lshl_add_u64 v[42:43], v[42:43], 0, v[122:123]
	s_mov_b32 s23, 0
	s_cmp_lt_i32 s21, 1
	s_mov_b32 s24, 0
	s_waitcnt vmcnt(5)
	ds_write_b128 v151, v[16:19]
	s_waitcnt vmcnt(4)
	ds_write2_b64 v187, v[20:21], v[22:23] offset1:2
	s_waitcnt vmcnt(3)
	ds_write_b128 v151, v[24:27] offset:10240
	s_waitcnt vmcnt(2)
	ds_write2_b64 v186, v[28:29], v[30:31] offset1:2
	s_waitcnt lgkmcnt(4)
	global_load_dwordx4 v[44:47], v[40:41], off offset:3072
	s_nop 0
	global_load_dwordx4 v[40:43], v[42:43], off
	s_cselect_b32 s91, 1, 0
	s_add_i32 s98, s90, -1
	s_ashr_i32 s98, s98, 6
	s_cmp_gt_i32 s98, 0
	s_cselect_b32 s99, 0x2000, 0
	s_cselect_b32 s98, 0x80, 0
	s_and_b32 s29, s73, 3
	s_lshl_b32 s29, s29, 1
	s_bfe_u32 s30, s73, 0x10002
	s_or_b32 s29, s29, s30
	s_bfe_u32 s30, s73, 0x10009
	s_xor_b32 s29, s29, s30
	s_lshl_b32 s29, s29, 16
	s_add_u32 s100, s3, s29
	s_addc_u32 s101, s52, 0
	s_add_u32 s30, s53, s29
	s_addc_u32 s31, s54, 0
	v_mov_b32_e32 v194, v134
	v_mov_b32_e32 v195, 0
	v_mov_b32_e32 v196, v136
	v_mov_b32_e32 v197, 0
	v_lshl_add_u64 v[198:199], s[100:101], 0, v[194:195]
	v_lshl_add_u64 v[200:201], s[30:31], 0, v[196:197]
	v_lshl_add_u64 v[198:199], v[198:199], 0, v[122:123]
	v_lshl_add_u64 v[200:201], v[200:201], 0, v[122:123]
	global_load_dwordx4 v[240:243], v[198:199], off
	global_load_dwordx4 v[244:247], v[200:201], off
	s_add_u32 s100, s100, s99
	s_addc_u32 s101, s101, 0
	s_add_u32 s30, s30, s98
	s_addc_u32 s31, s31, 0
	v_lshl_add_u64 v[198:199], s[100:101], 0, v[194:195]
	v_lshl_add_u64 v[200:201], s[30:31], 0, v[196:197]
	v_lshl_add_u64 v[198:199], v[198:199], 0, v[122:123]
	v_lshl_add_u64 v[200:201], v[200:201], 0, v[122:123]
	global_load_dwordx4 v[248:251], v[198:199], off
	global_load_dwordx4 v[252:255], v[200:201], off
	s_cmp_lg_u32 s91, 0
	s_waitcnt lgkmcnt(0)
	s_barrier
	s_cbranch_scc1 .LBB0_1068
	v_lshl_add_u64 v[16:17], s[0:1], 0, v[140:141]
	v_lshl_add_u64 v[106:107], v[16:17], 0, v[122:123]
	v_add_u32_e32 v16, s74, v171
	v_mov_b32_e32 v86, 0
	s_add_i32 s22, s74, 0xfffffe10
	v_subrev_u32_e32 v81, s20, v16
	v_mov_b32_e32 v87, v86
	v_mov_b32_e32 v88, v86
	v_mov_b32_e32 v89, v86
	s_mov_b32 s23, 5
	v_mov_b32_e32 v90, v86
	v_mov_b32_e32 v91, v86
	v_mov_b32_e32 v92, v86
	v_mov_b32_e32 v93, v86
	v_mov_b32_e32 v94, v86
	v_mov_b32_e32 v95, v86
	v_mov_b32_e32 v96, v86
	v_mov_b32_e32 v97, v86
	v_mov_b32_e32 v98, v86
	v_mov_b32_e32 v99, v86
	v_mov_b32_e32 v100, v86
	v_mov_b32_e32 v101, v86
	v_mov_b32_e32 v102, v86
	v_mov_b32_e32 v103, v86
	v_mov_b32_e32 v104, v86
	v_mov_b32_e32 v105, v86
